# P5 dynamic tile queue: next-index LDS broadcast written ahead of the existing pre-epilogue barrier (the extra barrier is gone)
# speedup vs baseline: 1.0087x; 1.0087x over previous
.LBB0_362:
	s_or_b64 exec, exec, s[38:39]
	s_waitcnt vmcnt(0)
	s_and_saveexec_b64 s[100:101], s[2:3]
	s_cbranch_execz .Lq5_nowrite
	v_mov_b32_e32 v251, 0x20600
	ds_write_b32 v251, v250
.Lq5_nowrite:
	s_or_b64 exec, exec, s[100:101]
	s_waitcnt lgkmcnt(0)
	s_barrier
	s_cmp_lt_i32 s99, 0
	s_cbranch_scc1 .Lp5_nosig
	s_and_saveexec_b64 s[100:101], s[2:3]
	s_cbranch_execz .Lp5_sig_done
	s_lshl_b32 s0, s99, 6
	s_add_u32 s0, s11, s0
	s_addc_u32 s1, s33, 0
	s_add_u32 s0, s0, 0x1000
	s_addc_u32 s1, s1, 0
	global_atomic_add v131, v153, s[0:1]

.Lp5_nosig:
	s_mov_b32 s99, s34
	v_mov_b32_e32 v251, 0x20600
	ds_read_b32 v251, v251
	s_waitcnt lgkmcnt(0)
	v_readfirstlane_b32 s54, v251
	s_nop 3
	s_cmpk_gt_i32 s54, 0x57f
	s_cselect_b64 s[38:39], -1, 0
	s_cmpk_lt_i32 s54, 0x580
	s_cselect_b64 s[0:1], -1, 0
	s_and_b64 s[0:1], s[2:3], s[0:1]
	s_and_saveexec_b64 s[40:41], s[0:1]
	s_cbranch_execz .LBB0_341
	s_mul_hi_i32 s0, s54, 0x2e8ba2e9
	s_lshr_b32 s1, s0, 31
	s_lshr_b32 s0, s0, 2
	s_add_i32 s0, s0, s1
	s_lshl_b32 s0, s0, 4
	s_ashr_i32 s1, s0, 31
	s_lshl_b64 s[0:1], s[0:1], 2
	s_add_u32 s46, s11, s0
	s_addc_u32 s47, s33, s1
	s_mov_b32 s35, 0x400001
	s_branch .LBB0_365
